# GEMM2 epilogue: the 8 ssq float atomics issued together at the end of the epilogue (values parked in dead fragment registers) so the per-step load waits no longer cover an atomic
# baseline (speedup 1.0000x reference)
; __device__ __forceinline__ unsigned cvt_pk_bf16(float lo, float hi) { unsigned r; asm volatile("v_cvt_pk_bf16_f32 %0, %1, %2" : "=v"(r) : "v"(lo), "v"(hi)); return r; }
;     __device__ __forceinline__ void operator()(const f32x4 (&acc)[2][2][4][2], const Unit& u, int wr, int wc, int fr, int fq) const {
;     ...
;             for (int m = 0; m < 4; ++m) { const int row = row0 + ai * HALF + m * 16; const size_t off = (size_t)row * ldc + col0; float ss = 0.f;
; #pragma unroll
;                 for (int bj = 0; bj < 2; ++bj) { const f32x4 v0 = *(const f32x4*)(base + off + bj * HALF) + acc[ai][bj][m][0], v1 = *(const f32x4*)(base + off + bj * HALF + 4) + acc[ai][bj][m][1];
;                     ss += (v0[0] * v0[0] + v0[1] * v0[1]) + (v0[2] * v0[2] + v0[3] * v0[3]) + (v1[0] * v1[0] + v1[1] * v1[1]) + (v1[2] * v1[2] + v1[3] * v1[3]);
;                     u32x4 w; w.x = cvt_pk_bf16(v0[0], v0[1]); w.y = cvt_pk_bf16(v0[2], v0[3]); w.z = cvt_pk_bf16(v1[0], v1[1]); w.w = cvt_pk_bf16(v1[2], v1[3]);
;                     *(u32x4*)(O + off + bj * HALF) = w; }
;                 ss += __shfl_xor(ss, 16); ss += __shfl_xor(ss, 32);
;                 if (fq == 0) atomicAdd(ssq + row, ss);
.LBB0_516:
	s_cmp_lg_u32 s9, 1
	s_cselect_b64 s[42:43], -1, 0
	s_lshl_b32 s12, s10, 8
	v_add_u32_e32 v4, s12, v160
	s_mov_b64 s[10:11], -1
	s_and_b64 vcc, exec, s[42:43]
	v_ashrrev_i32_e32 v5, 31, v4
	s_cbranch_vccz .LBB0_535
	v_lshl_or_b32 v152, s8, 8, v169
	v_ashrrev_i32_e32 v153, 31, v152
	v_lshlrev_b64 v[154:155], 12, v[4:5]
	v_lshl_add_u64 v[154:155], v[154:155], 0, v[152:153]
	v_lshl_add_u64 v[182:183], v[154:155], 2, s[18:19]
	global_load_dwordx4 v[174:177], v[182:183], off
	global_load_dwordx4 v[178:181], v[182:183], off offset:16
	v_lshl_add_u64 v[184:185], v[154:155], 1, s[22:23]
	v_xor_b32_e32 v3, 16, v173
	s_waitcnt vmcnt(0)
	v_pk_add_f32 v[154:155], v[132:133], v[176:177]
	v_pk_add_f32 v[186:187], v[130:131], v[174:175]
	v_pk_add_f32 v[190:191], v[128:129], v[180:181]
	v_pk_add_f32 v[192:193], v[126:127], v[178:179]
	v_cvt_pk_bf16_f32 v174, v186, v187
	v_cvt_pk_bf16_f32 v175, v154, v155
	v_mul_f32_e32 v155, v155, v155
	v_cvt_pk_bf16_f32 v176, v192, v193
	v_cvt_pk_bf16_f32 v177, v190, v191
	global_store_dwordx4 v[184:185], v[174:177], off
	global_load_dwordx4 v[174:177], v[182:183], off offset:512
	s_nop 0
	global_load_dwordx4 v[178:181], v[182:183], off offset:528
	v_and_b32_e32 v182, 64, v173
	v_add_u32_e32 v188, 64, v182
	v_mul_f32_e32 v182, v187, v187
	v_mul_f32_e32 v183, v193, v193
	v_fmac_f32_e32 v182, v186, v186
	v_fmac_f32_e32 v155, v154, v154
	v_mul_f32_e32 v187, v191, v191
	v_fmac_f32_e32 v183, v192, v192
	v_add_f32_e32 v154, v182, v155
	v_fmac_f32_e32 v187, v190, v190
	v_add_f32_e32 v154, v154, v183
	v_add_f32_e32 v186, v187, v154
	v_cmp_lt_i32_e32 vcc, v3, v188
	s_waitcnt vmcnt(1)
	v_pk_add_f32 v[182:183], v[100:101], v[176:177]
	v_pk_add_f32 v[154:155], v[98:99], v[174:175]
	s_waitcnt vmcnt(0)
	v_pk_add_f32 v[178:179], v[94:95], v[178:179]
	v_mul_f32_e32 v174, v155, v155
	v_mul_f32_e32 v175, v183, v183
	v_pk_add_f32 v[180:181], v[96:97], v[180:181]
	v_mul_f32_e32 v176, v179, v179
	v_fmac_f32_e32 v174, v154, v154
	v_fmac_f32_e32 v175, v182, v182
	v_mul_f32_e32 v177, v181, v181
	v_fmac_f32_e32 v176, v178, v178
	v_add_f32_e32 v174, v174, v175
	v_fmac_f32_e32 v177, v180, v180
	v_add_f32_e32 v174, v174, v176
	v_cndmask_b32_e32 v3, v173, v3, vcc
	v_add_f32_e32 v174, v177, v174
	v_lshlrev_b32_e32 v3, 2, v3
	v_add_f32_e32 v174, v186, v174
	ds_bpermute_b32 v175, v3, v174
	v_xor_b32_e32 v176, 32, v173
	v_cmp_lt_i32_e32 vcc, v176, v188
	s_nop 1
	v_cndmask_b32_e32 v177, v173, v176, vcc
	v_cvt_pk_bf16_f32 v176, v154, v155
	s_waitcnt lgkmcnt(0)
	v_add_f32_e32 v154, v174, v175
	v_lshlrev_b32_e32 v174, 2, v177
	ds_bpermute_b32 v155, v174, v154
	v_cvt_pk_bf16_f32 v177, v182, v183
	v_cvt_pk_bf16_f32 v178, v178, v179
	v_cvt_pk_bf16_f32 v179, v180, v181
	global_store_dwordx4 v[184:185], v[176:179], off offset:256
	s_and_saveexec_b64 s[8:9], s[4:5]
	s_cbranch_execz .LBB0_519
	v_lshl_add_u64 v[176:177], v[4:5], 2, s[24:25]
	s_waitcnt lgkmcnt(0)
	v_add_f32_e32 v154, v154, v155
	v_mov_b32_e32 v200, v154
.LBB0_519:
	s_or_b64 exec, exec, s[8:9]
	v_or_b32_e32 v154, 16, v4
	s_waitcnt lgkmcnt(0)
	v_ashrrev_i32_e32 v155, 31, v154
	v_lshlrev_b64 v[176:177], 12, v[154:155]
	v_lshl_add_u64 v[184:185], v[176:177], 0, v[152:153]
	v_lshl_add_u64 v[186:187], v[184:185], 2, s[18:19]
	global_load_dwordx4 v[176:179], v[186:187], off
	global_load_dwordx4 v[180:183], v[186:187], off offset:16
	v_lshl_add_u64 v[184:185], v[184:185], 1, s[22:23]
	s_waitcnt vmcnt(1)
	v_pk_add_f32 v[190:191], v[124:125], v[178:179]
	v_pk_add_f32 v[192:193], v[122:123], v[176:177]
	s_waitcnt vmcnt(0)
	v_pk_add_f32 v[196:197], v[120:121], v[182:183]
	v_pk_add_f32 v[198:199], v[118:119], v[180:181]
	v_cvt_pk_bf16_f32 v176, v192, v193
	v_cvt_pk_bf16_f32 v177, v190, v191
	v_mul_f32_e32 v175, v193, v193
	v_cvt_pk_bf16_f32 v178, v198, v199
	v_cvt_pk_bf16_f32 v179, v196, v197
	global_store_dwordx4 v[184:185], v[176:179], off
	global_load_dwordx4 v[176:179], v[186:187], off offset:512
	s_nop 0
	global_load_dwordx4 v[180:183], v[186:187], off offset:528
	v_mul_f32_e32 v186, v191, v191
	v_mul_f32_e32 v187, v199, v199
	v_fmac_f32_e32 v175, v192, v192
	v_fmac_f32_e32 v186, v190, v190
	v_fmac_f32_e32 v187, v198, v198
	v_add_f32_e32 v175, v175, v186
	v_mul_f32_e32 v188, v197, v197
	v_add_f32_e32 v175, v175, v187
	v_fmac_f32_e32 v188, v196, v196
	v_add_f32_e32 v175, v188, v175
	s_waitcnt vmcnt(1)
	v_pk_add_f32 v[186:187], v[92:93], v[178:179]
	v_pk_add_f32 v[176:177], v[90:91], v[176:177]
	s_waitcnt vmcnt(0)
	v_pk_add_f32 v[180:181], v[86:87], v[180:181]
	v_mul_f32_e32 v178, v177, v177
	v_mul_f32_e32 v179, v187, v187
	v_pk_add_f32 v[182:183], v[88:89], v[182:183]
	v_mul_f32_e32 v188, v181, v181
	v_fmac_f32_e32 v178, v176, v176
	v_fmac_f32_e32 v179, v186, v186
	v_mul_f32_e32 v190, v183, v183
	v_fmac_f32_e32 v188, v180, v180
	v_add_f32_e32 v178, v178, v179
	v_add_f32_e32 v178, v178, v188
	v_fmac_f32_e32 v190, v182, v182
	v_add_f32_e32 v178, v190, v178
	v_add_f32_e32 v175, v175, v178
	ds_bpermute_b32 v179, v3, v175
	v_cvt_pk_bf16_f32 v178, v176, v177
	s_waitcnt lgkmcnt(0)
	v_add_f32_e32 v175, v175, v179
	ds_bpermute_b32 v176, v174, v175
	v_cvt_pk_bf16_f32 v179, v186, v187
	v_cvt_pk_bf16_f32 v180, v180, v181
	v_cvt_pk_bf16_f32 v181, v182, v183
	global_store_dwordx4 v[184:185], v[178:181], off offset:256
	s_and_saveexec_b64 s[8:9], s[4:5]
	s_cbranch_execz .LBB0_521
	v_lshl_add_u64 v[154:155], v[154:155], 2, s[24:25]
	s_waitcnt lgkmcnt(0)
	v_add_f32_e32 v175, v175, v176
	v_mov_b32_e32 v201, v175
; __device__ __forceinline__ unsigned cvt_pk_bf16(float lo, float hi) { unsigned r; asm volatile("v_cvt_pk_bf16_f32 %0, %1, %2" : "=v"(r) : "v"(lo), "v"(hi)); return r; }
;     __device__ __forceinline__ void operator()(const f32x4 (&acc)[2][2][4][2], const Unit& u, int wr, int wc, int fr, int fq) const {
;     ...
;             for (int m = 0; m < 4; ++m) { const int row = row0 + ai * HALF + m * 16; const size_t off = (size_t)row * ldc + col0; float ss = 0.f;
; #pragma unroll
;                 for (int bj = 0; bj < 2; ++bj) { const f32x4 v0 = *(const f32x4*)(base + off + bj * HALF) + acc[ai][bj][m][0], v1 = *(const f32x4*)(base + off + bj * HALF + 4) + acc[ai][bj][m][1];
;                     ss += (v0[0] * v0[0] + v0[1] * v0[1]) + (v0[2] * v0[2] + v0[3] * v0[3]) + (v1[0] * v1[0] + v1[1] * v1[1]) + (v1[2] * v1[2] + v1[3] * v1[3]);
;                     u32x4 w; w.x = cvt_pk_bf16(v0[0], v0[1]); w.y = cvt_pk_bf16(v0[2], v0[3]); w.z = cvt_pk_bf16(v1[0], v1[1]); w.w = cvt_pk_bf16(v1[2], v1[3]);
;                     *(u32x4*)(O + off + bj * HALF) = w; }
;                 ss += __shfl_xor(ss, 16); ss += __shfl_xor(ss, 32);
;                 if (fq == 0) atomicAdd(ssq + row, ss);
;                 if (m & 1) asm volatile("" ::: "memory"); }
.LBB0_521:
	s_or_b64 exec, exec, s[8:9]
	v_or_b32_e32 v154, 32, v4
	v_ashrrev_i32_e32 v155, 31, v154
	s_waitcnt lgkmcnt(0)
	v_lshlrev_b64 v[176:177], 12, v[154:155]
	v_lshl_add_u64 v[184:185], v[176:177], 0, v[152:153]
	v_lshl_add_u64 v[186:187], v[184:185], 2, s[18:19]
	global_load_dwordx4 v[176:179], v[186:187], off
	global_load_dwordx4 v[180:183], v[186:187], off offset:16
	v_lshl_add_u64 v[184:185], v[184:185], 1, s[22:23]
	s_waitcnt vmcnt(1)
	v_pk_add_f32 v[190:191], v[116:117], v[178:179]
	v_pk_add_f32 v[192:193], v[114:115], v[176:177]
	s_waitcnt vmcnt(0)
	v_pk_add_f32 v[196:197], v[112:113], v[182:183]
	v_pk_add_f32 v[198:199], v[110:111], v[180:181]
	v_cvt_pk_bf16_f32 v176, v192, v193
	v_cvt_pk_bf16_f32 v177, v190, v191
	v_mul_f32_e32 v175, v193, v193
	v_cvt_pk_bf16_f32 v178, v198, v199
	v_cvt_pk_bf16_f32 v179, v196, v197
	global_store_dwordx4 v[184:185], v[176:179], off
	global_load_dwordx4 v[176:179], v[186:187], off offset:512
	s_nop 0
	global_load_dwordx4 v[180:183], v[186:187], off offset:528
	v_mul_f32_e32 v186, v191, v191
	v_mul_f32_e32 v187, v199, v199
	v_fmac_f32_e32 v175, v192, v192
	v_fmac_f32_e32 v186, v190, v190
	v_fmac_f32_e32 v187, v198, v198
	v_add_f32_e32 v175, v175, v186
	v_mul_f32_e32 v188, v197, v197
	v_add_f32_e32 v175, v175, v187
	v_fmac_f32_e32 v188, v196, v196
	v_add_f32_e32 v175, v188, v175
	s_waitcnt vmcnt(1)
	v_pk_add_f32 v[186:187], v[84:85], v[178:179]
	v_pk_add_f32 v[176:177], v[82:83], v[176:177]
	s_waitcnt vmcnt(0)
	v_pk_add_f32 v[180:181], v[78:79], v[180:181]
	v_mul_f32_e32 v178, v177, v177
	v_mul_f32_e32 v179, v187, v187
	v_pk_add_f32 v[182:183], v[80:81], v[182:183]
	v_mul_f32_e32 v188, v181, v181
	v_fmac_f32_e32 v178, v176, v176
	v_fmac_f32_e32 v179, v186, v186
	v_mul_f32_e32 v190, v183, v183
	v_fmac_f32_e32 v188, v180, v180
	v_add_f32_e32 v178, v178, v179
	v_add_f32_e32 v178, v178, v188
	v_fmac_f32_e32 v190, v182, v182
	v_add_f32_e32 v178, v190, v178
	v_add_f32_e32 v175, v175, v178
	ds_bpermute_b32 v179, v3, v175
	v_cvt_pk_bf16_f32 v178, v176, v177
	s_waitcnt lgkmcnt(0)
	v_add_f32_e32 v175, v175, v179
	ds_bpermute_b32 v176, v174, v175
	v_cvt_pk_bf16_f32 v179, v186, v187
	v_cvt_pk_bf16_f32 v180, v180, v181
	v_cvt_pk_bf16_f32 v181, v182, v183
	global_store_dwordx4 v[184:185], v[178:181], off offset:256
	s_and_saveexec_b64 s[8:9], s[4:5]
	s_cbranch_execz .LBB0_523
	v_lshl_add_u64 v[154:155], v[154:155], 2, s[24:25]
	s_waitcnt lgkmcnt(0)
	v_add_f32_e32 v175, v175, v176
	v_mov_b32_e32 v202, v175
.LBB0_523:
	s_or_b64 exec, exec, s[8:9]
	v_or_b32_e32 v154, 48, v4
	v_ashrrev_i32_e32 v155, 31, v154
	s_waitcnt lgkmcnt(0)
	v_lshlrev_b64 v[176:177], 12, v[154:155]
	v_lshl_add_u64 v[184:185], v[176:177], 0, v[152:153]
	v_lshl_add_u64 v[186:187], v[184:185], 2, s[18:19]
	global_load_dwordx4 v[176:179], v[186:187], off
	global_load_dwordx4 v[180:183], v[186:187], off offset:16
	v_lshl_add_u64 v[184:185], v[184:185], 1, s[22:23]
	s_waitcnt vmcnt(1)
	v_pk_add_f32 v[190:191], v[108:109], v[178:179]
	v_pk_add_f32 v[192:193], v[106:107], v[176:177]
	s_waitcnt vmcnt(0)
	v_pk_add_f32 v[196:197], v[104:105], v[182:183]
	v_pk_add_f32 v[198:199], v[102:103], v[180:181]
	v_cvt_pk_bf16_f32 v176, v192, v193
	v_cvt_pk_bf16_f32 v177, v190, v191
	v_mul_f32_e32 v175, v193, v193
	v_cvt_pk_bf16_f32 v178, v198, v199
	v_cvt_pk_bf16_f32 v179, v196, v197
	global_store_dwordx4 v[184:185], v[176:179], off
	global_load_dwordx4 v[176:179], v[186:187], off offset:512
	s_nop 0
	global_load_dwordx4 v[180:183], v[186:187], off offset:528
	v_mul_f32_e32 v186, v191, v191
	v_mul_f32_e32 v187, v199, v199
	v_fmac_f32_e32 v175, v192, v192
	v_fmac_f32_e32 v186, v190, v190
	v_fmac_f32_e32 v187, v198, v198
	v_add_f32_e32 v175, v175, v186
	v_mul_f32_e32 v188, v197, v197
	v_add_f32_e32 v175, v175, v187
	v_fmac_f32_e32 v188, v196, v196
	v_add_f32_e32 v175, v188, v175
	s_waitcnt vmcnt(1)
	v_pk_add_f32 v[186:187], v[76:77], v[178:179]
	v_pk_add_f32 v[176:177], v[74:75], v[176:177]
	s_waitcnt vmcnt(0)
	v_pk_add_f32 v[180:181], v[70:71], v[180:181]
	v_mul_f32_e32 v178, v177, v177
	v_mul_f32_e32 v179, v187, v187
	v_pk_add_f32 v[182:183], v[72:73], v[182:183]
	v_mul_f32_e32 v188, v181, v181
	v_fmac_f32_e32 v178, v176, v176
	v_fmac_f32_e32 v179, v186, v186
	v_mul_f32_e32 v190, v183, v183
	v_fmac_f32_e32 v188, v180, v180
	v_add_f32_e32 v178, v178, v179
	v_add_f32_e32 v178, v178, v188
	v_fmac_f32_e32 v190, v182, v182
	v_add_f32_e32 v178, v190, v178
	v_add_f32_e32 v175, v175, v178
	ds_bpermute_b32 v179, v3, v175
	v_cvt_pk_bf16_f32 v178, v176, v177
	s_waitcnt lgkmcnt(0)
	v_add_f32_e32 v175, v175, v179
	ds_bpermute_b32 v176, v174, v175
	v_cvt_pk_bf16_f32 v179, v186, v187
	v_cvt_pk_bf16_f32 v180, v180, v181
	v_cvt_pk_bf16_f32 v181, v182, v183
	global_store_dwordx4 v[184:185], v[178:181], off offset:256
	s_and_saveexec_b64 s[8:9], s[4:5]
	s_cbranch_execz .LBB0_525
	v_lshl_add_u64 v[154:155], v[154:155], 2, s[24:25]
	s_waitcnt lgkmcnt(0)
	v_add_f32_e32 v175, v175, v176
	v_mov_b32_e32 v203, v175
; __device__ __forceinline__ unsigned cvt_pk_bf16(float lo, float hi) { unsigned r; asm volatile("v_cvt_pk_bf16_f32 %0, %1, %2" : "=v"(r) : "v"(lo), "v"(hi)); return r; }
;     __device__ __forceinline__ void operator()(const f32x4 (&acc)[2][2][4][2], const Unit& u, int wr, int wc, int fr, int fq) const {
;     ...
;             for (int m = 0; m < 4; ++m) { const int row = row0 + ai * HALF + m * 16; const size_t off = (size_t)row * ldc + col0; float ss = 0.f;
; #pragma unroll
;                 for (int bj = 0; bj < 2; ++bj) { const f32x4 v0 = *(const f32x4*)(base + off + bj * HALF) + acc[ai][bj][m][0], v1 = *(const f32x4*)(base + off + bj * HALF + 4) + acc[ai][bj][m][1];
;                     ss += (v0[0] * v0[0] + v0[1] * v0[1]) + (v0[2] * v0[2] + v0[3] * v0[3]) + (v1[0] * v1[0] + v1[1] * v1[1]) + (v1[2] * v1[2] + v1[3] * v1[3]);
;                     u32x4 w; w.x = cvt_pk_bf16(v0[0], v0[1]); w.y = cvt_pk_bf16(v0[2], v0[3]); w.z = cvt_pk_bf16(v1[0], v1[1]); w.w = cvt_pk_bf16(v1[2], v1[3]);
;                     *(u32x4*)(O + off + bj * HALF) = w; }
;                 ss += __shfl_xor(ss, 16); ss += __shfl_xor(ss, 32);
;                 if (fq == 0) atomicAdd(ssq + row, ss);
;                 if (m & 1) asm volatile("" ::: "memory"); }
.LBB0_525:
	s_or_b64 exec, exec, s[8:9]
	v_add_u32_e32 v154, 0x80, v4
	v_ashrrev_i32_e32 v155, 31, v154
	s_waitcnt lgkmcnt(0)
	v_lshlrev_b64 v[176:177], 12, v[154:155]
	v_lshl_add_u64 v[184:185], v[176:177], 0, v[152:153]
	v_lshl_add_u64 v[186:187], v[184:185], 2, s[18:19]
	global_load_dwordx4 v[176:179], v[186:187], off
	global_load_dwordx4 v[180:183], v[186:187], off offset:16
	v_lshl_add_u64 v[184:185], v[184:185], 1, s[22:23]
	s_waitcnt vmcnt(1)
	v_pk_add_f32 v[190:191], v[68:69], v[178:179]
	v_pk_add_f32 v[192:193], v[66:67], v[176:177]
	s_waitcnt vmcnt(0)
	v_pk_add_f32 v[196:197], v[64:65], v[182:183]
	v_pk_add_f32 v[198:199], v[62:63], v[180:181]
	v_cvt_pk_bf16_f32 v176, v192, v193
	v_cvt_pk_bf16_f32 v177, v190, v191
	v_mul_f32_e32 v175, v193, v193
	v_cvt_pk_bf16_f32 v178, v198, v199
	v_cvt_pk_bf16_f32 v179, v196, v197
	global_store_dwordx4 v[184:185], v[176:179], off
	global_load_dwordx4 v[176:179], v[186:187], off offset:512
	s_nop 0
	global_load_dwordx4 v[180:183], v[186:187], off offset:528
	v_mul_f32_e32 v186, v191, v191
	v_mul_f32_e32 v187, v199, v199
	v_fmac_f32_e32 v175, v192, v192
	v_fmac_f32_e32 v186, v190, v190
	v_fmac_f32_e32 v187, v198, v198
	v_add_f32_e32 v175, v175, v186
	v_mul_f32_e32 v188, v197, v197
	v_add_f32_e32 v175, v175, v187
	v_fmac_f32_e32 v188, v196, v196
	v_add_f32_e32 v175, v188, v175
	s_waitcnt vmcnt(1)
	v_pk_add_f32 v[186:187], v[36:37], v[178:179]
	v_pk_add_f32 v[176:177], v[34:35], v[176:177]
	s_waitcnt vmcnt(0)
	v_pk_add_f32 v[180:181], v[30:31], v[180:181]
	v_mul_f32_e32 v178, v177, v177
	v_mul_f32_e32 v179, v187, v187
	v_pk_add_f32 v[182:183], v[32:33], v[182:183]
	v_mul_f32_e32 v188, v181, v181
	v_fmac_f32_e32 v178, v176, v176
	v_fmac_f32_e32 v179, v186, v186
	v_mul_f32_e32 v190, v183, v183
	v_fmac_f32_e32 v188, v180, v180
	v_add_f32_e32 v178, v178, v179
	v_add_f32_e32 v178, v178, v188
	v_fmac_f32_e32 v190, v182, v182
	v_add_f32_e32 v178, v190, v178
	v_add_f32_e32 v175, v175, v178
	ds_bpermute_b32 v179, v3, v175
	v_cvt_pk_bf16_f32 v178, v176, v177
	s_waitcnt lgkmcnt(0)
	v_add_f32_e32 v175, v175, v179
	ds_bpermute_b32 v176, v174, v175
	v_cvt_pk_bf16_f32 v179, v186, v187
	v_cvt_pk_bf16_f32 v180, v180, v181
	v_cvt_pk_bf16_f32 v181, v182, v183
	global_store_dwordx4 v[184:185], v[178:181], off offset:256
	s_and_saveexec_b64 s[8:9], s[4:5]
	s_cbranch_execz .LBB0_527
	v_lshl_add_u64 v[154:155], v[154:155], 2, s[24:25]
	s_waitcnt lgkmcnt(0)
	v_add_f32_e32 v175, v175, v176
	v_mov_b32_e32 v204, v175
.LBB0_527:
	s_or_b64 exec, exec, s[8:9]
	v_add_u32_e32 v154, 0x90, v4
	v_ashrrev_i32_e32 v155, 31, v154
	s_waitcnt lgkmcnt(0)
	v_lshlrev_b64 v[176:177], 12, v[154:155]
	v_lshl_add_u64 v[184:185], v[176:177], 0, v[152:153]
	v_lshl_add_u64 v[186:187], v[184:185], 2, s[18:19]
	global_load_dwordx4 v[176:179], v[186:187], off
	global_load_dwordx4 v[180:183], v[186:187], off offset:16
	v_lshl_add_u64 v[184:185], v[184:185], 1, s[22:23]
	s_waitcnt vmcnt(1)
	v_pk_add_f32 v[190:191], v[60:61], v[178:179]
	v_pk_add_f32 v[192:193], v[58:59], v[176:177]
	s_waitcnt vmcnt(0)
	v_pk_add_f32 v[196:197], v[56:57], v[182:183]
	v_pk_add_f32 v[198:199], v[54:55], v[180:181]
	v_cvt_pk_bf16_f32 v176, v192, v193
	v_cvt_pk_bf16_f32 v177, v190, v191
	v_mul_f32_e32 v175, v193, v193
	v_cvt_pk_bf16_f32 v178, v198, v199
	v_cvt_pk_bf16_f32 v179, v196, v197
	global_store_dwordx4 v[184:185], v[176:179], off
	global_load_dwordx4 v[176:179], v[186:187], off offset:512
	s_nop 0
	global_load_dwordx4 v[180:183], v[186:187], off offset:528
	v_mul_f32_e32 v186, v191, v191
	v_mul_f32_e32 v187, v199, v199
	v_fmac_f32_e32 v175, v192, v192
	v_fmac_f32_e32 v186, v190, v190
	v_fmac_f32_e32 v187, v198, v198
	v_add_f32_e32 v175, v175, v186
	v_mul_f32_e32 v188, v197, v197
	v_add_f32_e32 v175, v175, v187
	v_fmac_f32_e32 v188, v196, v196
	v_add_f32_e32 v175, v188, v175
	s_waitcnt vmcnt(1)
	v_pk_add_f32 v[186:187], v[28:29], v[178:179]
	v_pk_add_f32 v[176:177], v[26:27], v[176:177]
	s_waitcnt vmcnt(0)
	v_pk_add_f32 v[180:181], v[22:23], v[180:181]
	v_mul_f32_e32 v178, v177, v177
	v_mul_f32_e32 v179, v187, v187
	v_pk_add_f32 v[182:183], v[24:25], v[182:183]
	v_mul_f32_e32 v188, v181, v181
	v_fmac_f32_e32 v178, v176, v176
	v_fmac_f32_e32 v179, v186, v186
	v_mul_f32_e32 v190, v183, v183
	v_fmac_f32_e32 v188, v180, v180
	v_add_f32_e32 v178, v178, v179
	v_add_f32_e32 v178, v178, v188
	v_fmac_f32_e32 v190, v182, v182
	v_add_f32_e32 v178, v190, v178
	v_add_f32_e32 v175, v175, v178
	ds_bpermute_b32 v179, v3, v175
	v_cvt_pk_bf16_f32 v178, v176, v177
	s_waitcnt lgkmcnt(0)
	v_add_f32_e32 v175, v175, v179
	ds_bpermute_b32 v176, v174, v175
	v_cvt_pk_bf16_f32 v179, v186, v187
	v_cvt_pk_bf16_f32 v180, v180, v181
	v_cvt_pk_bf16_f32 v181, v182, v183
	global_store_dwordx4 v[184:185], v[178:181], off offset:256
	s_and_saveexec_b64 s[8:9], s[4:5]
	s_cbranch_execz .LBB0_529
	v_lshl_add_u64 v[154:155], v[154:155], 2, s[24:25]
	s_waitcnt lgkmcnt(0)
	v_add_f32_e32 v175, v175, v176
	v_mov_b32_e32 v205, v175
; __device__ __forceinline__ unsigned cvt_pk_bf16(float lo, float hi) { unsigned r; asm volatile("v_cvt_pk_bf16_f32 %0, %1, %2" : "=v"(r) : "v"(lo), "v"(hi)); return r; }
;     __device__ __forceinline__ void operator()(const f32x4 (&acc)[2][2][4][2], const Unit& u, int wr, int wc, int fr, int fq) const {
;     ...
;             for (int m = 0; m < 4; ++m) { const int row = row0 + ai * HALF + m * 16; const size_t off = (size_t)row * ldc + col0; float ss = 0.f;
; #pragma unroll
;                 for (int bj = 0; bj < 2; ++bj) { const f32x4 v0 = *(const f32x4*)(base + off + bj * HALF) + acc[ai][bj][m][0], v1 = *(const f32x4*)(base + off + bj * HALF + 4) + acc[ai][bj][m][1];
;                     ss += (v0[0] * v0[0] + v0[1] * v0[1]) + (v0[2] * v0[2] + v0[3] * v0[3]) + (v1[0] * v1[0] + v1[1] * v1[1]) + (v1[2] * v1[2] + v1[3] * v1[3]);
;                     u32x4 w; w.x = cvt_pk_bf16(v0[0], v0[1]); w.y = cvt_pk_bf16(v0[2], v0[3]); w.z = cvt_pk_bf16(v1[0], v1[1]); w.w = cvt_pk_bf16(v1[2], v1[3]);
;                     *(u32x4*)(O + off + bj * HALF) = w; }
;                 ss += __shfl_xor(ss, 16); ss += __shfl_xor(ss, 32);
;                 if (fq == 0) atomicAdd(ssq + row, ss);
;                 if (m & 1) asm volatile("" ::: "memory"); }
.LBB0_529:
	s_or_b64 exec, exec, s[8:9]
	v_add_u32_e32 v154, 0xa0, v4
	v_ashrrev_i32_e32 v155, 31, v154
	s_waitcnt lgkmcnt(0)
	v_lshlrev_b64 v[176:177], 12, v[154:155]
	v_lshl_add_u64 v[184:185], v[176:177], 0, v[152:153]
	v_lshl_add_u64 v[186:187], v[184:185], 2, s[18:19]
	global_load_dwordx4 v[176:179], v[186:187], off
	global_load_dwordx4 v[180:183], v[186:187], off offset:16
	v_lshl_add_u64 v[184:185], v[184:185], 1, s[22:23]
	s_waitcnt vmcnt(1)
	v_pk_add_f32 v[190:191], v[52:53], v[178:179]
	v_pk_add_f32 v[192:193], v[50:51], v[176:177]
	s_waitcnt vmcnt(0)
	v_pk_add_f32 v[196:197], v[48:49], v[182:183]
	v_pk_add_f32 v[198:199], v[46:47], v[180:181]
	v_cvt_pk_bf16_f32 v176, v192, v193
	v_cvt_pk_bf16_f32 v177, v190, v191
	v_mul_f32_e32 v175, v193, v193
	v_cvt_pk_bf16_f32 v178, v198, v199
	v_cvt_pk_bf16_f32 v179, v196, v197
	global_store_dwordx4 v[184:185], v[176:179], off
	global_load_dwordx4 v[176:179], v[186:187], off offset:512
	s_nop 0
	global_load_dwordx4 v[180:183], v[186:187], off offset:528
	v_mul_f32_e32 v186, v191, v191
	v_mul_f32_e32 v187, v199, v199
	v_fmac_f32_e32 v175, v192, v192
	v_fmac_f32_e32 v186, v190, v190
	v_fmac_f32_e32 v187, v198, v198
	v_add_f32_e32 v175, v175, v186
	v_mul_f32_e32 v188, v197, v197
	v_add_f32_e32 v175, v175, v187
	v_fmac_f32_e32 v188, v196, v196
	v_add_f32_e32 v175, v188, v175
	s_waitcnt vmcnt(1)
	v_pk_add_f32 v[186:187], v[20:21], v[178:179]
	v_pk_add_f32 v[176:177], v[18:19], v[176:177]
	s_waitcnt vmcnt(0)
	v_pk_add_f32 v[180:181], v[14:15], v[180:181]
	v_mul_f32_e32 v178, v177, v177
	v_mul_f32_e32 v179, v187, v187
	v_pk_add_f32 v[182:183], v[16:17], v[182:183]
	v_mul_f32_e32 v188, v181, v181
	v_fmac_f32_e32 v178, v176, v176
	v_fmac_f32_e32 v179, v186, v186
	v_mul_f32_e32 v190, v183, v183
	v_fmac_f32_e32 v188, v180, v180
	v_add_f32_e32 v178, v178, v179
	v_add_f32_e32 v178, v178, v188
	v_fmac_f32_e32 v190, v182, v182
	v_add_f32_e32 v178, v190, v178
	v_add_f32_e32 v175, v175, v178
	ds_bpermute_b32 v179, v3, v175
	v_cvt_pk_bf16_f32 v178, v176, v177
	s_waitcnt lgkmcnt(0)
	v_add_f32_e32 v175, v175, v179
	ds_bpermute_b32 v176, v174, v175
	v_cvt_pk_bf16_f32 v179, v186, v187
	v_cvt_pk_bf16_f32 v180, v180, v181
	v_cvt_pk_bf16_f32 v181, v182, v183
	global_store_dwordx4 v[184:185], v[178:181], off offset:256
	s_and_saveexec_b64 s[8:9], s[4:5]
	s_cbranch_execz .LBB0_531
	v_lshl_add_u64 v[154:155], v[154:155], 2, s[24:25]
	s_waitcnt lgkmcnt(0)
	v_add_f32_e32 v175, v175, v176
	v_mov_b32_e32 v206, v175
.LBB0_531:
	s_or_b64 exec, exec, s[8:9]
	v_add_u32_e32 v154, 0xb0, v4
	v_ashrrev_i32_e32 v155, 31, v154
	s_waitcnt lgkmcnt(0)
	v_lshlrev_b64 v[176:177], 12, v[154:155]
	v_lshl_add_u64 v[152:153], v[176:177], 0, v[152:153]
	v_lshl_add_u64 v[184:185], v[152:153], 2, s[18:19]
	global_load_dwordx4 v[176:179], v[184:185], off
	global_load_dwordx4 v[180:183], v[184:185], off offset:16
	v_lshl_add_u64 v[186:187], v[152:153], 1, s[22:23]
	s_waitcnt vmcnt(1)
	v_pk_add_f32 v[152:153], v[44:45], v[178:179]
	v_pk_add_f32 v[190:191], v[42:43], v[176:177]
	s_waitcnt vmcnt(0)
	v_pk_add_f32 v[192:193], v[40:41], v[182:183]
	v_pk_add_f32 v[196:197], v[38:39], v[180:181]
	v_cvt_pk_bf16_f32 v176, v190, v191
	v_cvt_pk_bf16_f32 v177, v152, v153
	v_mul_f32_e32 v175, v191, v191
	v_cvt_pk_bf16_f32 v178, v196, v197
	v_cvt_pk_bf16_f32 v179, v192, v193
	global_store_dwordx4 v[186:187], v[176:179], off
	global_load_dwordx4 v[176:179], v[184:185], off offset:512
	s_nop 0
	global_load_dwordx4 v[180:183], v[184:185], off offset:528
	v_mul_f32_e32 v153, v153, v153
	v_mul_f32_e32 v184, v197, v197
	v_fmac_f32_e32 v175, v190, v190
	v_fmac_f32_e32 v153, v152, v152
	v_mul_f32_e32 v185, v193, v193
	v_fmac_f32_e32 v184, v196, v196
	v_add_f32_e32 v152, v175, v153
	v_fmac_f32_e32 v185, v192, v192
	v_add_f32_e32 v152, v152, v184
	v_add_f32_e32 v175, v185, v152
	s_waitcnt vmcnt(1)
	v_pk_add_f32 v[178:179], v[12:13], v[178:179]
	v_pk_add_f32 v[152:153], v[10:11], v[176:177]
	s_waitcnt vmcnt(0)
	v_pk_add_f32 v[180:181], v[6:7], v[180:181]
	v_mul_f32_e32 v176, v153, v153
	v_mul_f32_e32 v177, v179, v179
	v_pk_add_f32 v[182:183], v[8:9], v[182:183]
	v_mul_f32_e32 v184, v181, v181
	v_fmac_f32_e32 v176, v152, v152
	v_fmac_f32_e32 v177, v178, v178
	v_mul_f32_e32 v185, v183, v183
	v_fmac_f32_e32 v184, v180, v180
	v_add_f32_e32 v176, v176, v177
	v_add_f32_e32 v176, v176, v184
	v_fmac_f32_e32 v185, v182, v182
	v_add_f32_e32 v176, v185, v176
	v_add_f32_e32 v175, v175, v176
	ds_bpermute_b32 v3, v3, v175
	v_cvt_pk_bf16_f32 v176, v152, v153
	v_cvt_pk_bf16_f32 v177, v178, v179
	v_cvt_pk_bf16_f32 v178, v180, v181
	v_cvt_pk_bf16_f32 v179, v182, v183
	s_waitcnt lgkmcnt(0)
	v_add_f32_e32 v3, v175, v3
	ds_bpermute_b32 v152, v174, v3
	global_store_dwordx4 v[186:187], v[176:179], off offset:256
	s_and_saveexec_b64 s[8:9], s[4:5]
	s_cbranch_execz .LBB0_533
	v_lshl_add_u64 v[154:155], v[154:155], 2, s[24:25]
	s_waitcnt lgkmcnt(0)
	v_add_f32_e32 v3, v3, v152
	v_mov_b32_e32 v207, v3
.LBB0_533:
	s_or_b64 exec, exec, s[8:9]
	s_and_saveexec_b64 s[8:9], s[4:5]
	s_cbranch_execz .Lg2_at_done
	v_lshl_add_u64 v[208:209], v[4:5], 2, s[24:25]
	global_atomic_add_f32 v[208:209], v200, off
	v_or_b32_e32 v208, 16, v4
	v_ashrrev_i32_e32 v209, 31, v208
	v_lshl_add_u64 v[208:209], v[208:209], 2, s[24:25]
	global_atomic_add_f32 v[208:209], v201, off
	v_or_b32_e32 v208, 32, v4
	v_ashrrev_i32_e32 v209, 31, v208
	v_lshl_add_u64 v[208:209], v[208:209], 2, s[24:25]
	global_atomic_add_f32 v[208:209], v202, off
	v_or_b32_e32 v208, 48, v4
	v_ashrrev_i32_e32 v209, 31, v208
	v_lshl_add_u64 v[208:209], v[208:209], 2, s[24:25]
	global_atomic_add_f32 v[208:209], v203, off
	v_add_u32_e32 v208, 0x80, v4
	v_ashrrev_i32_e32 v209, 31, v208
	v_lshl_add_u64 v[208:209], v[208:209], 2, s[24:25]
	global_atomic_add_f32 v[208:209], v204, off
	v_add_u32_e32 v208, 0x90, v4
	v_ashrrev_i32_e32 v209, 31, v208
	v_lshl_add_u64 v[208:209], v[208:209], 2, s[24:25]
	global_atomic_add_f32 v[208:209], v205, off
	v_add_u32_e32 v208, 0xa0, v4
	v_ashrrev_i32_e32 v209, 31, v208
	v_lshl_add_u64 v[208:209], v[208:209], 2, s[24:25]
	global_atomic_add_f32 v[208:209], v206, off
	v_add_u32_e32 v208, 0xb0, v4
	v_ashrrev_i32_e32 v209, 31, v208
	v_lshl_add_u64 v[208:209], v[208:209], 2, s[24:25]
	global_atomic_add_f32 v[208:209], v207, off
